# phase F epilogue: next batch merge-gate loads prefetched one batch ahead into K-loop fragment registers, vmcnt waits re-derived
# baseline (speedup 1.0000x reference)
.LBB0_596:
	s_lshl_b32 s5, s40, 8
	s_and_b32 s5, s5, 0x3f00
	s_ashr_i32 s4, s40, 6
	v_add_u32_e32 v184, s5, v192
	s_lshl_b32 s5, s20, 8
	s_and_b32 s5, s5, 0x700
	s_lshl_b32 s56, s4, 11
	v_mov_b64_e32 v[116:117], s[24:25]
	v_or_b32_e32 v130, s5, v194
	s_ashr_i32 s57, s56, 31
	v_mad_i64_i32 v[116:117], s[6:7], v184, s82, v[116:117]
	v_lshl_add_u64 v[116:117], s[56:57], 1, v[116:117]
	v_lshlrev_b32_e32 v168, 1, v130
	v_lshl_add_u64 v[130:131], v[116:117], 0, v[168:169]
	s_mov_b32 s100, 0x5a00
	s_mov_b32 s101, 0
	v_lshl_add_u64 v[238:239], v[130:131], 0, s[100:101]
	v_add_co_u32_e32 v116, vcc, 0x5000, v130
	v_ashrrev_i32_e32 v185, 31, v184
	s_nop 0
	v_addc_co_u32_e32 v117, vcc, 0, v131, vcc
	global_load_dwordx4 v[158:161], v[116:117], off offset:2560
	s_cmp_gt_i32 s4, 0
	v_lshlrev_b64 v[188:189], 12, v[184:185]
	s_cselect_b64 s[18:19], -1, 0
	s_cmp_lt_i32 s4, 1
	v_lshl_add_u64 v[116:117], s[42:43], 0, v[188:189]
	s_mov_b64 s[8:9], 0x5a00
	s_cbranch_scc1 .LBB0_598
	v_lshl_add_u64 v[132:133], v[116:117], 0, v[168:169]
	global_load_dwordx4 v[154:157], v[132:133], off
	s_branch .LBB0_599

.LBB0_605:
	s_mov_b32 s100, 0x114000
	v_lshl_add_u64 v[240:241], v[238:239], 0, s[100:101]
	global_load_dwordx4 v[222:225], v[240:241], off
	global_load_dwordx4 v[226:229], v[240:241], off offset:256
	s_mov_b32 s100, 0x19e000
	v_lshl_add_u64 v[240:241], v[238:239], 0, s[100:101]
	global_load_dwordx4 v[230:233], v[240:241], off
	global_load_dwordx4 v[234:237], v[240:241], off offset:256
	s_waitcnt vmcnt(4)
	v_lshlrev_b32_e32 v117, 16, v158
	v_mul_f32_e32 v117, 0xbfb8aa3b, v117
	v_exp_f32_e32 v117, v117
	s_cmp_lt_i32 s4, 2
	v_and_b32_e32 v158, 0xffff0000, v158
	v_mul_f32_e32 v158, 0xbfb8aa3b, v158
	v_add_f32_e32 v117, 1.0, v117
	v_div_scale_f32 v185, s[4:5], v117, v117, 1.0
	v_rcp_f32_e32 v190, v185
	v_div_scale_f32 v191, vcc, 1.0, v117, 1.0
	v_exp_f32_e32 v158, v158
	v_fma_f32 v196, -v185, v190, 1.0
	v_fmac_f32_e32 v190, v196, v190
	v_mul_f32_e32 v196, v191, v190
	v_fma_f32 v197, -v185, v196, v191
	v_add_f32_e32 v158, 1.0, v158
	v_rcp_f32_e32 v117, v117
	s_nop 0
	v_lshlrev_b32_e32 v185, 16, v154
	v_fmac_f32_e32 v185, v126, v117
	v_lshlrev_b32_e32 v196, 16, v159
	v_mul_f32_e32 v196, 0xbfb8aa3b, v196
	v_exp_f32_e32 v196, v196
	v_rcp_f32_e32 v117, v158
	s_nop 0
	v_add_f32_e32 v126, 1.0, v196
	v_div_scale_f32 v190, s[4:5], v126, v126, 1.0
	v_rcp_f32_e32 v191, v190
	v_and_b32_e32 v154, 0xffff0000, v154
	v_fmac_f32_e32 v154, v127, v117
	s_cselect_b32 s59, s43, s73
	v_fma_f32 v117, -v190, v191, 1.0
	v_fmac_f32_e32 v191, v117, v191
	v_and_b32_e32 v158, 0xffff0000, v159
	v_mul_f32_e32 v158, 0xbfb8aa3b, v158
	v_exp_f32_e32 v158, v158
	v_rcp_f32_e32 v117, v126
	s_nop 0
	v_add_f32_e32 v127, 1.0, v158
	v_lshlrev_b32_e32 v126, 16, v155
	v_fmac_f32_e32 v126, v128, v117
	s_cselect_b32 s58, s42, s72
	v_lshlrev_b32_e32 v190, 16, v160
	v_mul_f32_e32 v190, 0xbfb8aa3b, v190
	v_exp_f32_e32 v190, v190
	v_rcp_f32_e32 v117, v127
	s_nop 0
	v_add_f32_e32 v128, 1.0, v190
	v_and_b32_e32 v127, 0xffff0000, v155
	v_fmac_f32_e32 v127, v129, v117
	v_and_b32_e32 v155, 0xffff0000, v160
	v_mul_f32_e32 v155, 0xbfb8aa3b, v155
	v_exp_f32_e32 v155, v155
	v_rcp_f32_e32 v117, v128
	s_nop 0
	v_add_f32_e32 v129, 1.0, v155
	v_lshlrev_b32_e32 v128, 16, v156
	v_fmac_f32_e32 v128, v122, v117
	v_lshlrev_b32_e32 v159, 16, v161
	v_mul_f32_e32 v159, 0xbfb8aa3b, v159
	v_exp_f32_e32 v159, v159
	v_rcp_f32_e32 v117, v129
	s_nop 0
	v_add_f32_e32 v122, 1.0, v159
	v_and_b32_e32 v129, 0xffff0000, v156
	v_fmac_f32_e32 v129, v123, v117
	v_and_b32_e32 v156, 0xffff0000, v161
	v_mul_f32_e32 v156, 0xbfb8aa3b, v156
	v_exp_f32_e32 v156, v156
	v_rcp_f32_e32 v117, v122
	s_nop 0
	v_add_f32_e32 v123, 1.0, v156
	v_div_scale_f32 v155, s[4:5], v123, v123, 1.0
	v_rcp_f32_e32 v156, v155
	v_lshlrev_b32_e32 v158, 16, v157
	v_fmac_f32_e32 v158, v124, v117
	v_fma_f32 v117, -v155, v156, 1.0
	v_fmac_f32_e32 v156, v117, v156
	v_rcp_f32_e32 v117, v123
	s_nop 0
	v_and_b32_e32 v155, 0xffff0000, v157
	v_fmac_f32_e32 v155, v125, v117
	v_lshlrev_b32_e32 v117, 16, v150
	v_mul_f32_e32 v117, 0xbfb8aa3b, v117
	v_exp_f32_e32 v117, v117
	v_cvt_pk_bf16_f32 v124, v128, v129
	v_cvt_pk_bf16_f32 v122, v185, v154
	v_cvt_pk_bf16_f32 v125, v158, v155
	v_lshl_add_u64 v[154:155], s[58:59], 0, v[188:189]
	v_add_f32_e32 v117, 1.0, v117
	v_cvt_pk_bf16_f32 v123, v126, v127
	v_lshl_add_u64 v[126:127], v[154:155], 0, v[168:169]
	global_store_dwordx4 v[126:127], v[122:125], off
	s_nop 1
	v_and_b32_e32 v124, 0xffff0000, v150
	v_mul_f32_e32 v124, 0xbfb8aa3b, v124
	v_exp_f32_e32 v124, v124
	v_rcp_f32_e32 v117, v117
	s_nop 0
	v_add_f32_e32 v123, 1.0, v124
	v_lshlrev_b32_e32 v122, 16, v146
	v_fmac_f32_e32 v122, v118, v117
	v_lshlrev_b32_e32 v128, 16, v151
	v_mul_f32_e32 v128, 0xbfb8aa3b, v128
	v_exp_f32_e32 v128, v128
	v_rcp_f32_e32 v117, v123
	s_nop 0
	v_add_f32_e32 v118, 1.0, v128
	v_and_b32_e32 v123, 0xffff0000, v146
	v_fmac_f32_e32 v123, v119, v117
	v_and_b32_e32 v128, 0xffff0000, v151
	v_mul_f32_e32 v128, 0xbfb8aa3b, v128
	v_exp_f32_e32 v128, v128
	v_rcp_f32_e32 v117, v118
	s_nop 0
	v_add_f32_e32 v119, 1.0, v128
	v_lshlrev_b32_e32 v118, 16, v147
	v_fmac_f32_e32 v118, v120, v117
	v_lshlrev_b32_e32 v128, 16, v152
	v_mul_f32_e32 v128, 0xbfb8aa3b, v128
	v_exp_f32_e32 v128, v128
	v_rcp_f32_e32 v117, v119
	s_nop 0
	v_add_f32_e32 v120, 1.0, v128
	v_and_b32_e32 v119, 0xffff0000, v147
	v_fmac_f32_e32 v119, v121, v117
	v_and_b32_e32 v128, 0xffff0000, v152
	v_mul_f32_e32 v128, 0xbfb8aa3b, v128
	v_exp_f32_e32 v128, v128
	v_rcp_f32_e32 v117, v120
	s_nop 0
	v_add_f32_e32 v121, 1.0, v128
	v_lshlrev_b32_e32 v120, 16, v148
	v_fmac_f32_e32 v120, v112, v117
	v_lshlrev_b32_e32 v128, 16, v153
	v_mul_f32_e32 v128, 0xbfb8aa3b, v128
	v_exp_f32_e32 v128, v128
	v_rcp_f32_e32 v112, v121
	s_nop 0
	v_add_f32_e32 v117, 1.0, v128
	v_and_b32_e32 v121, 0xffff0000, v148
	v_fmac_f32_e32 v121, v113, v112
	v_and_b32_e32 v128, 0xffff0000, v153
	v_mul_f32_e32 v128, 0xbfb8aa3b, v128
	v_exp_f32_e32 v128, v128
	v_rcp_f32_e32 v112, v117
	s_nop 0
	v_add_f32_e32 v113, 1.0, v128
	v_div_scale_f32 v124, s[4:5], v113, v113, 1.0
	v_rcp_f32_e32 v125, v124
	v_lshlrev_b32_e32 v117, 16, v149
	v_fmac_f32_e32 v117, v114, v112
	v_fma_f32 v112, -v124, v125, 1.0
	v_fmac_f32_e32 v125, v112, v125
	v_rcp_f32_e32 v112, v113
	s_nop 0
	v_lshlrev_b32_e32 v113, 16, v142
	v_mul_f32_e32 v113, 0xbfb8aa3b, v113
	v_exp_f32_e32 v114, v113
	v_cvt_pk_bf16_f32 v113, v118, v119
	v_and_b32_e32 v124, 0xffff0000, v149
	v_fmac_f32_e32 v124, v115, v112
	v_add_f32_e32 v118, 1.0, v114
	v_div_scale_f32 v119, s[4:5], v118, v118, 1.0
	v_cvt_pk_bf16_f32 v112, v122, v123
	v_rcp_f32_e32 v122, v119
	v_cvt_pk_bf16_f32 v114, v120, v121
	v_cvt_pk_bf16_f32 v115, v117, v124
	global_store_dwordx4 v[126:127], v[112:115], off offset:256
	v_lshlrev_b32_e32 v117, 16, v138
	s_nop 0
	v_fma_f32 v112, -v119, v122, 1.0
	v_fmac_f32_e32 v122, v112, v122
	v_and_b32_e32 v114, 0xffff0000, v142
	v_mul_f32_e32 v114, 0xbfb8aa3b, v114
	v_exp_f32_e32 v114, v114
	v_rcp_f32_e32 v112, v118
	s_nop 0
	v_add_f32_e32 v113, 1.0, v114
	v_fmac_f32_e32 v117, v108, v112
	v_lshlrev_b32_e32 v118, 16, v143
	v_mul_f32_e32 v118, 0xbfb8aa3b, v118
	v_exp_f32_e32 v118, v118
	v_rcp_f32_e32 v108, v113
	s_nop 0
	v_add_f32_e32 v112, 1.0, v118
	v_and_b32_e32 v113, 0xffff0000, v138
	v_fmac_f32_e32 v113, v109, v108
	v_and_b32_e32 v118, 0xffff0000, v143
	v_mul_f32_e32 v118, 0xbfb8aa3b, v118
	v_exp_f32_e32 v118, v118
	v_rcp_f32_e32 v108, v112
	s_nop 0
	v_add_f32_e32 v109, 1.0, v118
	v_lshlrev_b32_e32 v112, 16, v139
	v_fmac_f32_e32 v112, v110, v108
	v_lshlrev_b32_e32 v118, 16, v144
	v_mul_f32_e32 v118, 0xbfb8aa3b, v118
	v_exp_f32_e32 v118, v118
	v_rcp_f32_e32 v108, v109
	s_nop 0
	v_add_f32_e32 v110, 1.0, v118
	v_and_b32_e32 v109, 0xffff0000, v139
	v_fmac_f32_e32 v109, v111, v108
	v_and_b32_e32 v118, 0xffff0000, v144
	v_mul_f32_e32 v118, 0xbfb8aa3b, v118
	v_exp_f32_e32 v118, v118
	v_rcp_f32_e32 v108, v110
	s_nop 0
	v_add_f32_e32 v111, 1.0, v118
	v_lshlrev_b32_e32 v110, 16, v140
	v_fmac_f32_e32 v110, v104, v108
	v_lshlrev_b32_e32 v118, 16, v145
	v_mul_f32_e32 v118, 0xbfb8aa3b, v118
	v_exp_f32_e32 v118, v118
	v_rcp_f32_e32 v104, v111
	s_nop 0
	v_add_f32_e32 v108, 1.0, v118
	v_and_b32_e32 v111, 0xffff0000, v140
	v_fmac_f32_e32 v111, v105, v104
	v_and_b32_e32 v118, 0xffff0000, v145
	v_mul_f32_e32 v118, 0xbfb8aa3b, v118
	v_exp_f32_e32 v118, v118
	v_rcp_f32_e32 v104, v108
	s_nop 0
	v_add_f32_e32 v105, 1.0, v118
	v_div_scale_f32 v114, s[4:5], v105, v105, 1.0
	v_rcp_f32_e32 v115, v114
	v_lshlrev_b32_e32 v108, 16, v141
	v_fmac_f32_e32 v108, v106, v104
	v_fma_f32 v104, -v114, v115, 1.0
	v_fmac_f32_e32 v115, v104, v115
	v_div_scale_f32 v104, vcc, 1.0, v105, 1.0
	v_mul_f32_e32 v106, v104, v115
	v_fma_f32 v118, -v114, v106, v104
	v_rcp_f32_e32 v104, v105
	s_nop 0
	v_lshlrev_b32_e32 v105, 16, v134
	v_and_b32_e32 v114, 0xffff0000, v141
	v_mul_f32_e32 v105, 0xbfb8aa3b, v105
	v_fmac_f32_e32 v114, v107, v104
	v_cvt_pk_bf16_f32 v104, v117, v113
	v_exp_f32_e32 v113, v105
	v_cvt_pk_bf16_f32 v106, v110, v111
	v_cvt_pk_bf16_f32 v105, v112, v109
	v_cvt_pk_bf16_f32 v107, v108, v114
	v_lshl_add_u64 v[108:109], s[58:59], 0, v[186:187]
	v_add_f32_e32 v110, 1.0, v113
	v_div_scale_f32 v111, s[4:5], v110, v110, 1.0
	v_rcp_f32_e32 v112, v111
	v_lshl_add_u64 v[108:109], v[108:109], 0, v[168:169]
	global_store_dwordx4 v[108:109], v[104:107], off
	v_mov_b32_e32 v117, 0
	v_mov_b32_e32 v114, 0
	v_fma_f32 v104, -v111, v112, 1.0
	v_fmac_f32_e32 v112, v104, v112
	v_and_b32_e32 v106, 0xffff0000, v134
	v_mul_f32_e32 v106, 0xbfb8aa3b, v106
	v_exp_f32_e32 v106, v106
	v_rcp_f32_e32 v104, v110
	s_nop 0
	v_add_f32_e32 v105, 1.0, v106
	v_lshlrev_b32_e32 v110, 16, v130
	v_fmac_f32_e32 v110, v100, v104
	v_mov_b32_e32 v115, 0
	v_lshlrev_b32_e32 v111, 16, v135
	v_mul_f32_e32 v111, 0xbfb8aa3b, v111
	v_exp_f32_e32 v111, v111
	v_rcp_f32_e32 v100, v105
	s_nop 0
	v_add_f32_e32 v104, 1.0, v111
	v_and_b32_e32 v105, 0xffff0000, v130
	v_fmac_f32_e32 v105, v101, v100
	v_and_b32_e32 v111, 0xffff0000, v135
	v_mul_f32_e32 v111, 0xbfb8aa3b, v111
	v_exp_f32_e32 v111, v111
	v_rcp_f32_e32 v100, v104
	s_nop 0
	v_add_f32_e32 v101, 1.0, v111
	v_lshlrev_b32_e32 v104, 16, v131
	v_fmac_f32_e32 v104, v102, v100
	v_lshlrev_b32_e32 v111, 16, v136
	v_mul_f32_e32 v111, 0xbfb8aa3b, v111
	v_exp_f32_e32 v111, v111
	v_rcp_f32_e32 v100, v101
	s_nop 0
	v_add_f32_e32 v102, 1.0, v111
	v_and_b32_e32 v101, 0xffff0000, v131
	v_fmac_f32_e32 v101, v103, v100
	v_and_b32_e32 v111, 0xffff0000, v136
	v_mul_f32_e32 v111, 0xbfb8aa3b, v111
	v_exp_f32_e32 v111, v111
	v_rcp_f32_e32 v100, v102
	s_nop 0
	v_add_f32_e32 v103, 1.0, v111
	v_lshlrev_b32_e32 v102, 16, v132
	v_fmac_f32_e32 v102, v96, v100
	v_lshlrev_b32_e32 v111, 16, v137
	v_mul_f32_e32 v111, 0xbfb8aa3b, v111
	v_exp_f32_e32 v111, v111
	v_rcp_f32_e32 v96, v103
	s_nop 0
	v_add_f32_e32 v100, 1.0, v111
	v_and_b32_e32 v103, 0xffff0000, v132
	v_fmac_f32_e32 v103, v97, v96
	v_and_b32_e32 v111, 0xffff0000, v137
	v_mul_f32_e32 v111, 0xbfb8aa3b, v111
	v_exp_f32_e32 v111, v111
	v_rcp_f32_e32 v96, v100
	s_nop 0
	v_add_f32_e32 v97, 1.0, v111
	v_div_scale_f32 v106, s[4:5], v97, v97, 1.0
	v_rcp_f32_e32 v107, v106
	v_lshlrev_b32_e32 v100, 16, v133
	v_fmac_f32_e32 v100, v98, v96
	v_fma_f32 v96, -v106, v107, 1.0
	v_fmac_f32_e32 v107, v96, v107
	v_div_scale_f32 v96, vcc, 1.0, v97, 1.0
	v_mul_f32_e32 v98, v96, v107
	v_fma_f32 v111, -v106, v98, v96
	v_rcp_f32_e32 v96, v97
	s_nop 0
	v_and_b32_e32 v106, 0xffff0000, v133
	v_fmac_f32_e32 v106, v99, v96
	v_cvt_pk_bf16_f32 v96, v110, v105
	v_cvt_pk_bf16_f32 v98, v102, v103
	v_cvt_pk_bf16_f32 v99, v100, v106
	v_cvt_pk_bf16_f32 v97, v104, v101
	global_store_dwordx4 v[108:109], v[96:99], off offset:256
	s_nop 1
	v_or_b32_e32 v96, 32, v184
	v_mov_b64_e32 v[98:99], s[24:25]
	v_mad_i64_i32 v[98:99], s[4:5], v96, s82, v[98:99]
	v_lshl_add_u64 v[98:99], s[56:57], 1, v[98:99]
	v_lshl_add_u64 v[98:99], v[98:99], 0, v[168:169]
	v_add_co_u32_e32 v100, vcc, 0x5000, v98
	v_ashrrev_i32_e32 v97, 31, v96
	s_nop 0
	v_addc_co_u32_e32 v101, vcc, 0, v99, vcc
	s_waitcnt vmcnt(4)
	v_mov_b32_e32 v126, v222
	v_mov_b32_e32 v127, v223
	v_mov_b32_e32 v128, v224
	v_mov_b32_e32 v129, v225
	v_lshlrev_b64 v[132:133], 12, v[96:97]
	s_and_b64 vcc, exec, s[40:41]
	v_lshl_add_u64 v[96:97], s[42:43], 0, v[132:133]
	s_cbranch_vccnz .LBB0_607
	v_lshl_add_u64 v[100:101], v[96:97], 0, v[168:169]
	global_load_dwordx4 v[114:117], v[100:101], off
.LBB0_607:
	v_lshl_add_u64 v[98:99], v[98:99], 0, s[8:9]
	v_mov_b32_e32 v122, v226
	v_mov_b32_e32 v123, v227
	v_mov_b32_e32 v124, v228
	v_mov_b32_e32 v125, v229
	v_mov_b32_e32 v108, 0
	s_and_b64 vcc, exec, s[40:41]
	v_mov_b32_e32 v120, 0
	v_mov_b32_e32 v121, 0
	v_mov_b32_e32 v118, 0
	v_mov_b32_e32 v119, 0
	s_cbranch_vccnz .LBB0_609
	v_lshl_add_u64 v[96:97], v[96:97], 0, v[168:169]
	global_load_dwordx4 v[118:121], v[96:97], off offset:256
.LBB0_609:
	v_or_b32_e32 v98, 48, v184
	v_mov_b64_e32 v[96:97], s[24:25]
	v_mad_i64_i32 v[96:97], s[4:5], v98, s82, v[96:97]
	v_lshl_add_u64 v[96:97], s[56:57], 1, v[96:97]
	v_lshl_add_u64 v[96:97], v[96:97], 0, v[168:169]
	v_add_co_u32_e32 v100, vcc, 0x5000, v96
	v_ashrrev_i32_e32 v99, 31, v98
	s_nop 0
	v_addc_co_u32_e32 v101, vcc, 0, v97, vcc
	v_mov_b32_e32 v110, v230
	v_mov_b32_e32 v111, v231
	v_mov_b32_e32 v112, v232
	v_mov_b32_e32 v113, v233
	v_lshlrev_b64 v[130:131], 12, v[98:99]
	s_and_b64 vcc, exec, s[40:41]
	v_lshl_add_u64 v[134:135], s[42:43], 0, v[130:131]
	v_mov_b32_e32 v109, 0
	v_mov_b32_e32 v106, 0
	v_mov_b32_e32 v107, 0
	s_cbranch_vccnz .LBB0_611
	v_lshl_add_u64 v[98:99], v[134:135], 0, v[168:169]
	global_load_dwordx4 v[106:109], v[98:99], off
.LBB0_611:
	v_lshl_add_u64 v[96:97], v[96:97], 0, s[8:9]
	v_mov_b32_e32 v102, v234
	v_mov_b32_e32 v103, v235
	v_mov_b32_e32 v104, v236
	v_mov_b32_e32 v105, v237
	v_mov_b32_e32 v96, 0
	s_and_b64 vcc, exec, s[40:41]
	v_mov_b32_e32 v100, 0
	v_mov_b32_e32 v101, 0
	v_mov_b32_e32 v98, 0
	v_mov_b32_e32 v99, 0
	s_cbranch_vccnz .LBB0_613
	v_lshl_add_u64 v[98:99], v[134:135], 0, v[168:169]
	global_load_dwordx4 v[98:101], v[98:99], off offset:256
.LBB0_613:
	s_mov_b32 s100, 0x450000
	v_lshl_add_u64 v[240:241], v[238:239], 0, s[100:101]
	global_load_dwordx4 v[222:225], v[240:241], off
	global_load_dwordx4 v[226:229], v[240:241], off offset:256
	s_mov_b32 s100, 0x4da000
	v_lshl_add_u64 v[240:241], v[238:239], 0, s[100:101]
	global_load_dwordx4 v[230:233], v[240:241], off
	global_load_dwordx4 v[234:237], v[240:241], off offset:256
	s_waitcnt vmcnt(6)
	v_lshlrev_b32_e32 v97, 16, v126
	v_mul_f32_e32 v97, 0xbfb8aa3b, v97
	v_exp_f32_e32 v97, v97
	v_and_b32_e32 v126, 0xffff0000, v126
	v_mul_f32_e32 v126, 0xbfb8aa3b, v126
	v_exp_f32_e32 v126, v126
	v_add_f32_e32 v97, 1.0, v97
	v_div_scale_f32 v134, s[4:5], v97, v97, 1.0
	v_rcp_f32_e32 v135, v134
	v_div_scale_f32 v136, vcc, 1.0, v97, 1.0
	v_add_f32_e32 v126, 1.0, v126
	v_fma_f32 v137, -v134, v135, 1.0
	v_fmac_f32_e32 v135, v137, v135
	v_mul_f32_e32 v137, v136, v135
	v_fma_f32 v138, -v134, v137, v136
	v_rcp_f32_e32 v97, v97
	s_nop 0
	v_lshlrev_b32_e32 v134, 16, v114
	v_fmac_f32_e32 v134, v92, v97
	v_lshlrev_b32_e32 v137, 16, v127
	v_mul_f32_e32 v137, 0xbfb8aa3b, v137
	v_exp_f32_e32 v137, v137
	v_rcp_f32_e32 v92, v126
	s_nop 0
	v_add_f32_e32 v97, 1.0, v137
	v_div_scale_f32 v135, s[4:5], v97, v97, 1.0
	v_rcp_f32_e32 v136, v135
	v_and_b32_e32 v114, 0xffff0000, v114
	v_fmac_f32_e32 v114, v93, v92
	v_fma_f32 v92, -v135, v136, 1.0
	v_fmac_f32_e32 v136, v92, v136
	v_and_b32_e32 v126, 0xffff0000, v127
	v_mul_f32_e32 v126, 0xbfb8aa3b, v126
	v_exp_f32_e32 v126, v126
	v_rcp_f32_e32 v92, v97
	s_nop 0
	v_add_f32_e32 v93, 1.0, v126
	v_lshlrev_b32_e32 v97, 16, v115
	v_fmac_f32_e32 v97, v94, v92
	v_lshlrev_b32_e32 v135, 16, v128
	v_mul_f32_e32 v135, 0xbfb8aa3b, v135
	v_exp_f32_e32 v135, v135
	v_rcp_f32_e32 v92, v93
	s_nop 0
	v_add_f32_e32 v94, 1.0, v135
	v_and_b32_e32 v93, 0xffff0000, v115
	v_fmac_f32_e32 v93, v95, v92
	v_and_b32_e32 v115, 0xffff0000, v128
	v_mul_f32_e32 v115, 0xbfb8aa3b, v115
	v_exp_f32_e32 v115, v115
	v_rcp_f32_e32 v92, v94
	s_nop 0
	v_add_f32_e32 v95, 1.0, v115
	v_lshlrev_b32_e32 v94, 16, v116
	v_fmac_f32_e32 v94, v88, v92
	v_lshlrev_b32_e32 v127, 16, v129
	v_mul_f32_e32 v127, 0xbfb8aa3b, v127
	v_exp_f32_e32 v127, v127
	v_rcp_f32_e32 v88, v95
	s_nop 0
	v_add_f32_e32 v92, 1.0, v127
	v_and_b32_e32 v95, 0xffff0000, v116
	v_fmac_f32_e32 v95, v89, v88
	v_and_b32_e32 v116, 0xffff0000, v129
	v_mul_f32_e32 v116, 0xbfb8aa3b, v116
	v_exp_f32_e32 v116, v116
	v_rcp_f32_e32 v88, v92
	s_nop 0
	v_add_f32_e32 v89, 1.0, v116
	v_div_scale_f32 v115, s[4:5], v89, v89, 1.0
	v_rcp_f32_e32 v116, v115
	v_lshlrev_b32_e32 v92, 16, v117
	v_fmac_f32_e32 v92, v90, v88
	v_fma_f32 v88, -v115, v116, 1.0
	v_fmac_f32_e32 v116, v88, v116
	v_div_scale_f32 v88, vcc, 1.0, v89, 1.0
	v_mul_f32_e32 v90, v88, v116
	v_fma_f32 v126, -v115, v90, v88
	v_rcp_f32_e32 v88, v89
	s_nop 0
	s_waitcnt vmcnt(5)
	v_lshlrev_b32_e32 v89, 16, v122
	v_and_b32_e32 v115, 0xffff0000, v117
	v_mul_f32_e32 v89, 0xbfb8aa3b, v89
	v_fmac_f32_e32 v115, v91, v88
	v_cvt_pk_bf16_f32 v88, v134, v114
	v_exp_f32_e32 v114, v89
	v_cvt_pk_bf16_f32 v90, v94, v95
	v_cvt_pk_bf16_f32 v89, v97, v93
	v_cvt_pk_bf16_f32 v91, v92, v115
	v_lshl_add_u64 v[92:93], s[58:59], 0, v[132:133]
	v_add_f32_e32 v94, 1.0, v114
	v_lshl_add_u64 v[92:93], v[92:93], 0, v[168:169]
	global_store_dwordx4 v[92:93], v[88:91], off
	s_nop 1
	v_and_b32_e32 v90, 0xffff0000, v122
	v_mul_f32_e32 v90, 0xbfb8aa3b, v90
	v_exp_f32_e32 v90, v90
	v_rcp_f32_e32 v88, v94
	s_nop 0
	v_add_f32_e32 v89, 1.0, v90
	v_lshlrev_b32_e32 v94, 16, v118
	v_fmac_f32_e32 v94, v84, v88
	v_mov_b32_e32 v97, 0
	v_lshlrev_b32_e32 v95, 16, v123
	v_mul_f32_e32 v95, 0xbfb8aa3b, v95
	v_exp_f32_e32 v95, v95
	v_rcp_f32_e32 v84, v89
	s_nop 0
	v_add_f32_e32 v88, 1.0, v95
	v_and_b32_e32 v89, 0xffff0000, v118
	v_fmac_f32_e32 v89, v85, v84
	v_and_b32_e32 v95, 0xffff0000, v123
	v_mul_f32_e32 v95, 0xbfb8aa3b, v95
	v_exp_f32_e32 v95, v95
	v_rcp_f32_e32 v84, v88
	s_nop 0
	v_add_f32_e32 v85, 1.0, v95
	v_lshlrev_b32_e32 v88, 16, v119
	v_fmac_f32_e32 v88, v86, v84
	v_lshlrev_b32_e32 v95, 16, v124
	v_mul_f32_e32 v95, 0xbfb8aa3b, v95
	v_exp_f32_e32 v95, v95
	v_rcp_f32_e32 v84, v85
	s_nop 0
	v_add_f32_e32 v86, 1.0, v95
	v_and_b32_e32 v85, 0xffff0000, v119
	v_fmac_f32_e32 v85, v87, v84
	v_and_b32_e32 v95, 0xffff0000, v124
	v_mul_f32_e32 v95, 0xbfb8aa3b, v95
	v_exp_f32_e32 v95, v95
	v_rcp_f32_e32 v84, v86
	s_nop 0
	v_add_f32_e32 v87, 1.0, v95
	v_lshlrev_b32_e32 v86, 16, v120
	v_fmac_f32_e32 v86, v80, v84
	v_lshlrev_b32_e32 v95, 16, v125
	v_mul_f32_e32 v95, 0xbfb8aa3b, v95
	v_exp_f32_e32 v95, v95
	v_rcp_f32_e32 v80, v87
	s_nop 0
	v_add_f32_e32 v84, 1.0, v95
	v_and_b32_e32 v87, 0xffff0000, v120
	v_fmac_f32_e32 v87, v81, v80
	v_and_b32_e32 v95, 0xffff0000, v125
	v_mul_f32_e32 v95, 0xbfb8aa3b, v95
	v_exp_f32_e32 v95, v95
	v_rcp_f32_e32 v80, v84
	s_nop 0
	v_add_f32_e32 v81, 1.0, v95
	v_lshlrev_b32_e32 v84, 16, v121
	v_fmac_f32_e32 v84, v82, v80
	v_rcp_f32_e32 v80, v81
	s_nop 0
	s_waitcnt vmcnt(6)
	v_lshlrev_b32_e32 v81, 16, v110
	v_mul_f32_e32 v81, 0xbfb8aa3b, v81
	v_exp_f32_e32 v82, v81
	v_cvt_pk_bf16_f32 v81, v88, v85
	v_and_b32_e32 v90, 0xffff0000, v121
	v_fmac_f32_e32 v90, v83, v80
	v_add_f32_e32 v85, 1.0, v82
	v_div_scale_f32 v88, s[4:5], v85, v85, 1.0
	v_cvt_pk_bf16_f32 v80, v94, v89
	v_rcp_f32_e32 v89, v88
	v_cvt_pk_bf16_f32 v82, v86, v87
	v_cvt_pk_bf16_f32 v83, v84, v90
	global_store_dwordx4 v[92:93], v[80:83], off offset:256
	v_lshlrev_b32_e32 v84, 16, v106
	v_mov_b32_e32 v94, 0
	v_fma_f32 v80, -v88, v89, 1.0
	v_fmac_f32_e32 v89, v80, v89
	v_and_b32_e32 v82, 0xffff0000, v110
	v_mul_f32_e32 v82, 0xbfb8aa3b, v82
	v_exp_f32_e32 v82, v82
	v_rcp_f32_e32 v80, v85
	s_nop 0
	v_add_f32_e32 v81, 1.0, v82
	v_fmac_f32_e32 v84, v76, v80
	v_mov_b32_e32 v95, 0
	v_lshlrev_b32_e32 v85, 16, v111
	v_mul_f32_e32 v85, 0xbfb8aa3b, v85
	v_exp_f32_e32 v85, v85
	v_rcp_f32_e32 v76, v81
	s_nop 0
	v_add_f32_e32 v80, 1.0, v85
	v_and_b32_e32 v81, 0xffff0000, v106
	v_fmac_f32_e32 v81, v77, v76
	v_and_b32_e32 v85, 0xffff0000, v111
	v_mul_f32_e32 v85, 0xbfb8aa3b, v85
	v_exp_f32_e32 v85, v85
	v_rcp_f32_e32 v76, v80
	s_nop 0
	v_add_f32_e32 v77, 1.0, v85
	v_lshlrev_b32_e32 v80, 16, v107
	v_fmac_f32_e32 v80, v78, v76
	v_lshlrev_b32_e32 v85, 16, v112
	v_mul_f32_e32 v85, 0xbfb8aa3b, v85
	v_exp_f32_e32 v85, v85
	v_rcp_f32_e32 v76, v77
	s_nop 0
	v_add_f32_e32 v78, 1.0, v85
	v_and_b32_e32 v77, 0xffff0000, v107
	v_fmac_f32_e32 v77, v79, v76
	v_and_b32_e32 v85, 0xffff0000, v112
	v_mul_f32_e32 v85, 0xbfb8aa3b, v85
	v_exp_f32_e32 v85, v85
	v_rcp_f32_e32 v76, v78
	s_nop 0
	v_add_f32_e32 v79, 1.0, v85
	v_lshlrev_b32_e32 v78, 16, v108
	v_fmac_f32_e32 v78, v72, v76
	v_lshlrev_b32_e32 v85, 16, v113
	v_mul_f32_e32 v85, 0xbfb8aa3b, v85
	v_exp_f32_e32 v85, v85
	v_rcp_f32_e32 v72, v79
	s_nop 0
	v_add_f32_e32 v76, 1.0, v85
	v_and_b32_e32 v79, 0xffff0000, v108
	v_fmac_f32_e32 v79, v73, v72
	v_and_b32_e32 v85, 0xffff0000, v113
	v_mul_f32_e32 v85, 0xbfb8aa3b, v85
	v_exp_f32_e32 v85, v85
	v_rcp_f32_e32 v72, v76
	s_nop 0
	v_add_f32_e32 v73, 1.0, v85
	v_div_scale_f32 v82, s[4:5], v73, v73, 1.0
	v_rcp_f32_e32 v83, v82
	v_lshlrev_b32_e32 v76, 16, v109
	v_fmac_f32_e32 v76, v74, v72
	v_fma_f32 v72, -v82, v83, 1.0
	v_fmac_f32_e32 v83, v72, v83
	v_div_scale_f32 v72, vcc, 1.0, v73, 1.0
	v_mul_f32_e32 v74, v72, v83
	v_fma_f32 v85, -v82, v74, v72
	v_rcp_f32_e32 v72, v73
	s_nop 0
	s_waitcnt vmcnt(6)
	v_lshlrev_b32_e32 v73, 16, v102
	v_and_b32_e32 v82, 0xffff0000, v109
	v_mul_f32_e32 v73, 0xbfb8aa3b, v73
	v_fmac_f32_e32 v82, v75, v72
	v_cvt_pk_bf16_f32 v72, v84, v81
	v_exp_f32_e32 v81, v73
	v_cvt_pk_bf16_f32 v74, v78, v79
	v_cvt_pk_bf16_f32 v73, v80, v77
	v_cvt_pk_bf16_f32 v75, v76, v82
	v_lshl_add_u64 v[76:77], s[58:59], 0, v[130:131]
	v_add_f32_e32 v78, 1.0, v81
	v_div_scale_f32 v79, s[4:5], v78, v78, 1.0
	v_rcp_f32_e32 v80, v79
	v_lshl_add_u64 v[76:77], v[76:77], 0, v[168:169]
	global_store_dwordx4 v[76:77], v[72:75], off
	s_nop 1
	v_fma_f32 v72, -v79, v80, 1.0
	v_fmac_f32_e32 v80, v72, v80
	v_and_b32_e32 v74, 0xffff0000, v102
	v_mul_f32_e32 v74, 0xbfb8aa3b, v74
	v_exp_f32_e32 v74, v74
	v_rcp_f32_e32 v72, v78
	s_nop 0
	v_add_f32_e32 v73, 1.0, v74
	v_lshlrev_b32_e32 v78, 16, v98
	v_fmac_f32_e32 v78, v68, v72
	v_lshlrev_b32_e32 v79, 16, v103
	v_mul_f32_e32 v79, 0xbfb8aa3b, v79
	v_exp_f32_e32 v79, v79
	v_rcp_f32_e32 v68, v73
	s_nop 0
	v_add_f32_e32 v72, 1.0, v79
	v_and_b32_e32 v73, 0xffff0000, v98
	v_fmac_f32_e32 v73, v69, v68
	v_and_b32_e32 v79, 0xffff0000, v103
	v_mul_f32_e32 v79, 0xbfb8aa3b, v79
	v_exp_f32_e32 v79, v79
	v_rcp_f32_e32 v68, v72
	s_nop 0
	v_add_f32_e32 v69, 1.0, v79
	v_lshlrev_b32_e32 v72, 16, v99
	v_fmac_f32_e32 v72, v70, v68
	v_lshlrev_b32_e32 v79, 16, v104
	v_mul_f32_e32 v79, 0xbfb8aa3b, v79
	v_exp_f32_e32 v79, v79
	v_rcp_f32_e32 v68, v69
	s_nop 0
	v_add_f32_e32 v70, 1.0, v79
	v_and_b32_e32 v69, 0xffff0000, v99
	v_fmac_f32_e32 v69, v71, v68
	v_and_b32_e32 v79, 0xffff0000, v104
	v_mul_f32_e32 v79, 0xbfb8aa3b, v79
	v_exp_f32_e32 v79, v79
	v_rcp_f32_e32 v68, v70
	s_nop 0
	v_add_f32_e32 v71, 1.0, v79
	v_lshlrev_b32_e32 v70, 16, v100
	v_fmac_f32_e32 v70, v64, v68
	v_lshlrev_b32_e32 v79, 16, v105
	v_mul_f32_e32 v79, 0xbfb8aa3b, v79
	v_exp_f32_e32 v79, v79
	v_rcp_f32_e32 v64, v71
	s_nop 0
	v_add_f32_e32 v68, 1.0, v79
	v_and_b32_e32 v71, 0xffff0000, v100
	v_fmac_f32_e32 v71, v65, v64
	v_and_b32_e32 v79, 0xffff0000, v105
	v_mul_f32_e32 v79, 0xbfb8aa3b, v79
	v_exp_f32_e32 v79, v79
	v_rcp_f32_e32 v64, v68
	s_nop 0
	v_add_f32_e32 v65, 1.0, v79
	v_div_scale_f32 v74, s[4:5], v65, v65, 1.0
	v_rcp_f32_e32 v75, v74
	v_lshlrev_b32_e32 v68, 16, v101
	v_fmac_f32_e32 v68, v66, v64
	v_fma_f32 v64, -v74, v75, 1.0
	v_fmac_f32_e32 v75, v64, v75
	v_div_scale_f32 v64, vcc, 1.0, v65, 1.0
	v_mul_f32_e32 v66, v64, v75
	v_fma_f32 v79, -v74, v66, v64
	v_rcp_f32_e32 v64, v65
	s_nop 0
	v_and_b32_e32 v74, 0xffff0000, v101
	v_fmac_f32_e32 v74, v67, v64
	v_cvt_pk_bf16_f32 v64, v78, v73
	v_cvt_pk_bf16_f32 v66, v70, v71
	v_cvt_pk_bf16_f32 v67, v68, v74
	v_cvt_pk_bf16_f32 v65, v72, v69
	global_store_dwordx4 v[76:77], v[64:67], off offset:256
	s_nop 1
	v_add_u32_e32 v64, 0x80, v184
	v_mov_b64_e32 v[66:67], s[24:25]
	v_mad_i64_i32 v[66:67], s[4:5], v64, s82, v[66:67]
	v_lshl_add_u64 v[66:67], s[56:57], 1, v[66:67]
	v_lshl_add_u64 v[68:69], v[66:67], 0, v[168:169]
	v_add_co_u32_e32 v66, vcc, 0x5000, v68
	v_ashrrev_i32_e32 v65, 31, v64
	s_nop 0
	v_addc_co_u32_e32 v67, vcc, 0, v69, vcc
	s_waitcnt vmcnt(4)
	v_mov_b32_e32 v90, v222
	v_mov_b32_e32 v91, v223
	v_mov_b32_e32 v92, v224
	v_mov_b32_e32 v93, v225
	v_lshlrev_b64 v[98:99], 12, v[64:65]
	s_and_b64 vcc, exec, s[40:41]
	v_lshl_add_u64 v[66:67], s[42:43], 0, v[98:99]
	s_cbranch_vccnz .LBB0_615
	v_lshl_add_u64 v[70:71], v[66:67], 0, v[168:169]
	global_load_dwordx4 v[94:97], v[70:71], off
.LBB0_615:
	v_lshl_add_u64 v[68:69], v[68:69], 0, s[8:9]
	v_mov_b32_e32 v86, v226
	v_mov_b32_e32 v87, v227
	v_mov_b32_e32 v88, v228
	v_mov_b32_e32 v89, v229
	v_mov_b32_e32 v76, 0
	s_and_b64 vcc, exec, s[40:41]
	v_mov_b32_e32 v84, 0
	v_mov_b32_e32 v85, 0
	v_mov_b32_e32 v82, 0
	v_mov_b32_e32 v83, 0
	s_cbranch_vccnz .LBB0_617
	v_lshl_add_u64 v[66:67], v[66:67], 0, v[168:169]
	global_load_dwordx4 v[82:85], v[66:67], off offset:256
.LBB0_617:
	v_or_b32_e32 v66, 16, v64
	v_mov_b64_e32 v[64:65], s[24:25]
	v_mad_i64_i32 v[64:65], s[4:5], v66, s82, v[64:65]
	v_lshl_add_u64 v[64:65], s[56:57], 1, v[64:65]
	v_lshl_add_u64 v[64:65], v[64:65], 0, v[168:169]
	v_add_co_u32_e32 v68, vcc, 0x5000, v64
	v_ashrrev_i32_e32 v67, 31, v66
	s_nop 0
	v_addc_co_u32_e32 v69, vcc, 0, v65, vcc
	v_mov_b32_e32 v78, v230
	v_mov_b32_e32 v79, v231
	v_mov_b32_e32 v80, v232
	v_mov_b32_e32 v81, v233
	v_lshlrev_b64 v[66:67], 12, v[66:67]
	s_and_b64 vcc, exec, s[40:41]
	v_lshl_add_u64 v[100:101], s[42:43], 0, v[66:67]
	v_mov_b32_e32 v77, 0
	v_mov_b32_e32 v74, 0
	v_mov_b32_e32 v75, 0
	s_cbranch_vccnz .LBB0_619
	v_lshl_add_u64 v[66:67], v[100:101], 0, v[168:169]
	global_load_dwordx4 v[74:77], v[66:67], off
.LBB0_619:
	v_lshl_add_u64 v[64:65], v[64:65], 0, s[8:9]
	v_mov_b32_e32 v70, v234
	v_mov_b32_e32 v71, v235
	v_mov_b32_e32 v72, v236
	v_mov_b32_e32 v73, v237
	v_mov_b32_e32 v64, 0
	s_and_b64 vcc, exec, s[40:41]
	v_mov_b32_e32 v68, 0
	v_mov_b32_e32 v69, 0
	v_mov_b32_e32 v66, 0
	v_mov_b32_e32 v67, 0
	s_cbranch_vccnz .LBB0_621
	v_lshl_add_u64 v[66:67], v[100:101], 0, v[168:169]
	global_load_dwordx4 v[66:69], v[66:67], off offset:256
.LBB0_621:
	s_mov_b32 s100, 0x564000
	v_lshl_add_u64 v[240:241], v[238:239], 0, s[100:101]
	global_load_dwordx4 v[222:225], v[240:241], off
	global_load_dwordx4 v[226:229], v[240:241], off offset:256
	s_mov_b32 s100, 0x5ee000
	v_lshl_add_u64 v[240:241], v[238:239], 0, s[100:101]
	global_load_dwordx4 v[230:233], v[240:241], off
	global_load_dwordx4 v[234:237], v[240:241], off offset:256
	s_waitcnt vmcnt(6)
	v_lshlrev_b32_e32 v65, 16, v90
	v_mul_f32_e32 v65, 0xbfb8aa3b, v65
	v_exp_f32_e32 v65, v65
	v_and_b32_e32 v90, 0xffff0000, v90
	v_mul_f32_e32 v90, 0xbfb8aa3b, v90
	v_exp_f32_e32 v90, v90
	v_add_f32_e32 v65, 1.0, v65
	v_div_scale_f32 v100, s[4:5], v65, v65, 1.0
	v_rcp_f32_e32 v101, v100
	v_div_scale_f32 v102, vcc, 1.0, v65, 1.0
	v_add_f32_e32 v90, 1.0, v90
	v_fma_f32 v103, -v100, v101, 1.0
	v_fmac_f32_e32 v101, v103, v101
	v_mul_f32_e32 v103, v102, v101
	v_fma_f32 v104, -v100, v103, v102
	v_rcp_f32_e32 v65, v65
	s_nop 0
	v_lshlrev_b32_e32 v100, 16, v94
	v_fmac_f32_e32 v100, v60, v65
	v_lshlrev_b32_e32 v103, 16, v91
	v_mul_f32_e32 v103, 0xbfb8aa3b, v103
	v_exp_f32_e32 v103, v103
	v_rcp_f32_e32 v60, v90
	s_nop 0
	v_add_f32_e32 v65, 1.0, v103
	v_div_scale_f32 v101, s[4:5], v65, v65, 1.0
	v_rcp_f32_e32 v102, v101
	v_and_b32_e32 v90, 0xffff0000, v94
	v_fmac_f32_e32 v90, v61, v60
	v_and_b32_e32 v91, 0xffff0000, v91
	v_fma_f32 v60, -v101, v102, 1.0
	v_fmac_f32_e32 v102, v60, v102
	v_mul_f32_e32 v91, 0xbfb8aa3b, v91
	v_exp_f32_e32 v91, v91
	s_nop 0
	v_add_f32_e32 v61, 1.0, v91
	v_rcp_f32_e32 v60, v65
	s_nop 0
	v_lshlrev_b32_e32 v65, 16, v95
	v_fmac_f32_e32 v65, v62, v60
	v_lshlrev_b32_e32 v101, 16, v92
	v_mul_f32_e32 v101, 0xbfb8aa3b, v101
	v_exp_f32_e32 v101, v101
	v_rcp_f32_e32 v60, v61
	s_nop 0
	v_add_f32_e32 v62, 1.0, v101
	v_div_scale_f32 v91, s[4:5], v62, v62, 1.0
	v_rcp_f32_e32 v94, v91
	v_and_b32_e32 v61, 0xffff0000, v95
	v_fmac_f32_e32 v61, v63, v60
	v_and_b32_e32 v92, 0xffff0000, v92
	v_fma_f32 v60, -v91, v94, 1.0
	v_fmac_f32_e32 v94, v60, v94
	v_div_scale_f32 v60, vcc, 1.0, v62, 1.0
	v_mul_f32_e32 v92, 0xbfb8aa3b, v92
	v_mul_f32_e32 v63, v60, v94
	v_exp_f32_e32 v92, v92
	v_fma_f32 v95, -v91, v63, v60
	v_add_f32_e32 v63, 1.0, v92
	v_rcp_f32_e32 v60, v62
	s_nop 0
	v_lshlrev_b32_e32 v62, 16, v96
	v_fmac_f32_e32 v62, v56, v60
	v_lshlrev_b32_e32 v94, 16, v93
	v_mul_f32_e32 v94, 0xbfb8aa3b, v94
	v_exp_f32_e32 v94, v94
	v_rcp_f32_e32 v56, v63
	s_nop 0
	v_add_f32_e32 v60, 1.0, v94
	v_div_scale_f32 v91, s[4:5], v60, v60, 1.0
	v_rcp_f32_e32 v92, v91
	v_and_b32_e32 v63, 0xffff0000, v96
	v_fmac_f32_e32 v63, v57, v56
	v_and_b32_e32 v93, 0xffff0000, v93
	v_fma_f32 v56, -v91, v92, 1.0
	v_fmac_f32_e32 v92, v56, v92
	v_div_scale_f32 v56, vcc, 1.0, v60, 1.0
	v_mul_f32_e32 v93, 0xbfb8aa3b, v93
	v_mul_f32_e32 v57, v56, v92
	v_exp_f32_e32 v93, v93
	v_fma_f32 v94, -v91, v57, v56
	v_add_f32_e32 v57, 1.0, v93
	v_div_scale_f32 v91, s[4:5], v57, v57, 1.0
	v_rcp_f32_e32 v92, v91
	v_rcp_f32_e32 v56, v60
	s_nop 0
	v_lshlrev_b32_e32 v60, 16, v97
	v_fmac_f32_e32 v60, v58, v56
	v_fma_f32 v56, -v91, v92, 1.0
	v_fmac_f32_e32 v92, v56, v92
	v_div_scale_f32 v56, vcc, 1.0, v57, 1.0
	v_mul_f32_e32 v58, v56, v92
	v_fma_f32 v93, -v91, v58, v56
	v_rcp_f32_e32 v56, v57
	s_nop 0
	s_waitcnt vmcnt(5)
	v_lshlrev_b32_e32 v57, 16, v86
	v_and_b32_e32 v91, 0xffff0000, v97
	v_mul_f32_e32 v57, 0xbfb8aa3b, v57
	v_fmac_f32_e32 v91, v59, v56
	v_cvt_pk_bf16_f32 v56, v100, v90
	v_exp_f32_e32 v90, v57
	v_cvt_pk_bf16_f32 v58, v62, v63
	v_cvt_pk_bf16_f32 v57, v65, v61
	v_cvt_pk_bf16_f32 v59, v60, v91
	v_lshl_add_u64 v[60:61], s[58:59], 0, v[98:99]
	v_add_f32_e32 v62, 1.0, v90
	v_lshl_add_u64 v[60:61], v[60:61], 0, v[168:169]
	global_store_dwordx4 v[60:61], v[56:59], off
	s_nop 1
	v_and_b32_e32 v58, 0xffff0000, v86
	v_mul_f32_e32 v58, 0xbfb8aa3b, v58
	v_exp_f32_e32 v58, v58
	v_rcp_f32_e32 v56, v62
	s_nop 0
	v_add_f32_e32 v57, 1.0, v58
	v_lshlrev_b32_e32 v62, 16, v82
	v_fmac_f32_e32 v62, v52, v56
	v_mov_b32_e32 v65, 0
	v_lshlrev_b32_e32 v63, 16, v87
	v_mul_f32_e32 v63, 0xbfb8aa3b, v63
	v_exp_f32_e32 v63, v63
	v_rcp_f32_e32 v52, v57
	s_nop 0
	v_add_f32_e32 v56, 1.0, v63
	v_and_b32_e32 v57, 0xffff0000, v82
	v_fmac_f32_e32 v57, v53, v52
	v_and_b32_e32 v63, 0xffff0000, v87
	v_mul_f32_e32 v63, 0xbfb8aa3b, v63
	v_exp_f32_e32 v63, v63
	v_rcp_f32_e32 v52, v56
	s_nop 0
	v_add_f32_e32 v53, 1.0, v63
	v_lshlrev_b32_e32 v56, 16, v83
	v_fmac_f32_e32 v56, v54, v52
	v_lshlrev_b32_e32 v63, 16, v88
	v_mul_f32_e32 v63, 0xbfb8aa3b, v63
	v_exp_f32_e32 v63, v63
	v_rcp_f32_e32 v52, v53
	s_nop 0
	v_add_f32_e32 v54, 1.0, v63
	v_and_b32_e32 v53, 0xffff0000, v83
	v_fmac_f32_e32 v53, v55, v52
	v_and_b32_e32 v63, 0xffff0000, v88
	v_mul_f32_e32 v63, 0xbfb8aa3b, v63
	v_exp_f32_e32 v63, v63
	v_rcp_f32_e32 v52, v54
	s_nop 0
	v_add_f32_e32 v55, 1.0, v63
	v_lshlrev_b32_e32 v54, 16, v84
	v_fmac_f32_e32 v54, v48, v52
	v_lshlrev_b32_e32 v63, 16, v89
	v_mul_f32_e32 v63, 0xbfb8aa3b, v63
	v_exp_f32_e32 v63, v63
	v_rcp_f32_e32 v48, v55
	s_nop 0
	v_add_f32_e32 v52, 1.0, v63
	v_and_b32_e32 v55, 0xffff0000, v84
	v_fmac_f32_e32 v55, v49, v48
	v_and_b32_e32 v63, 0xffff0000, v89
	v_mul_f32_e32 v63, 0xbfb8aa3b, v63
	v_exp_f32_e32 v63, v63
	v_rcp_f32_e32 v48, v52
	s_nop 0
	v_add_f32_e32 v49, 1.0, v63
	v_lshlrev_b32_e32 v52, 16, v85
	v_fmac_f32_e32 v52, v50, v48
	v_rcp_f32_e32 v48, v49
	s_nop 0
	s_waitcnt vmcnt(6)
	v_lshlrev_b32_e32 v49, 16, v78
	v_mul_f32_e32 v49, 0xbfb8aa3b, v49
	v_exp_f32_e32 v50, v49
	v_cvt_pk_bf16_f32 v49, v56, v53
	v_and_b32_e32 v58, 0xffff0000, v85
	v_fmac_f32_e32 v58, v51, v48
	v_add_f32_e32 v53, 1.0, v50
	v_cvt_pk_bf16_f32 v48, v62, v57
	v_cvt_pk_bf16_f32 v50, v54, v55
	v_cvt_pk_bf16_f32 v51, v52, v58
	global_store_dwordx4 v[60:61], v[48:51], off offset:256
	v_lshlrev_b32_e32 v52, 16, v74
	v_mov_b32_e32 v62, 0
	v_and_b32_e32 v50, 0xffff0000, v78
	v_mul_f32_e32 v50, 0xbfb8aa3b, v50
	v_exp_f32_e32 v50, v50
	v_rcp_f32_e32 v48, v53
	s_nop 0
	v_add_f32_e32 v49, 1.0, v50
	v_fmac_f32_e32 v52, v44, v48
	v_mov_b32_e32 v63, 0
	v_lshlrev_b32_e32 v53, 16, v79
	v_mul_f32_e32 v53, 0xbfb8aa3b, v53
	v_exp_f32_e32 v53, v53
	v_rcp_f32_e32 v44, v49
	s_nop 0
	v_add_f32_e32 v48, 1.0, v53
	v_and_b32_e32 v49, 0xffff0000, v74
	v_fmac_f32_e32 v49, v45, v44
	v_and_b32_e32 v53, 0xffff0000, v79
	v_mul_f32_e32 v53, 0xbfb8aa3b, v53
	v_exp_f32_e32 v53, v53
	v_rcp_f32_e32 v44, v48
	s_nop 0
	v_add_f32_e32 v45, 1.0, v53
	v_lshlrev_b32_e32 v48, 16, v75
	v_fmac_f32_e32 v48, v46, v44
	v_lshlrev_b32_e32 v53, 16, v80
	v_mul_f32_e32 v53, 0xbfb8aa3b, v53
	v_exp_f32_e32 v53, v53
	v_rcp_f32_e32 v44, v45
	s_nop 0
	v_add_f32_e32 v46, 1.0, v53
	v_and_b32_e32 v45, 0xffff0000, v75
	v_fmac_f32_e32 v45, v47, v44
	v_and_b32_e32 v53, 0xffff0000, v80
	v_mul_f32_e32 v53, 0xbfb8aa3b, v53
	v_exp_f32_e32 v53, v53
	v_rcp_f32_e32 v44, v46
	s_nop 0
	v_add_f32_e32 v47, 1.0, v53
	v_lshlrev_b32_e32 v46, 16, v76
	v_fmac_f32_e32 v46, v40, v44
	v_lshlrev_b32_e32 v53, 16, v81
	v_mul_f32_e32 v53, 0xbfb8aa3b, v53
	v_exp_f32_e32 v53, v53
	v_rcp_f32_e32 v40, v47
	s_nop 0
	v_add_f32_e32 v44, 1.0, v53
	v_and_b32_e32 v47, 0xffff0000, v76
	v_fmac_f32_e32 v47, v41, v40
	v_and_b32_e32 v53, 0xffff0000, v81
	v_mul_f32_e32 v53, 0xbfb8aa3b, v53
	v_exp_f32_e32 v53, v53
	v_rcp_f32_e32 v40, v44
	s_nop 0
	v_add_f32_e32 v41, 1.0, v53
	v_div_scale_f32 v50, s[4:5], v41, v41, 1.0
	v_rcp_f32_e32 v51, v50
	v_lshlrev_b32_e32 v44, 16, v77
	v_fmac_f32_e32 v44, v42, v40
	s_mov_b64 s[4:5], 0x90000
	v_fma_f32 v40, -v50, v51, 1.0
	v_fmac_f32_e32 v51, v40, v51
	v_div_scale_f32 v40, vcc, 1.0, v41, 1.0
	v_mul_f32_e32 v42, v40, v51
	v_fma_f32 v53, -v50, v42, v40
	v_rcp_f32_e32 v40, v41
	s_nop 0
	v_and_b32_e32 v50, 0xffff0000, v77
	v_fmac_f32_e32 v50, v43, v40
	s_waitcnt vmcnt(6)
	v_lshlrev_b32_e32 v43, 16, v70
	v_mul_f32_e32 v43, 0xbfb8aa3b, v43
	v_cvt_pk_bf16_f32 v41, v48, v45
	v_exp_f32_e32 v48, v43
	v_cvt_pk_bf16_f32 v43, v44, v50
	v_lshl_add_u64 v[44:45], v[154:155], 0, v[168:169]
	v_cvt_pk_bf16_f32 v40, v52, v49
	v_add_f32_e32 v48, 1.0, v48
	v_cvt_pk_bf16_f32 v42, v46, v47
	v_lshl_add_u64 v[46:47], v[44:45], 0, s[4:5]
	v_div_scale_f32 v49, s[4:5], v48, v48, 1.0
	v_rcp_f32_e32 v50, v49
	s_mov_b32 s4, 0x90000
	v_add_co_u32_e32 v44, vcc, s4, v44
	s_nop 1
	v_addc_co_u32_e32 v45, vcc, 0, v45, vcc
	global_store_dwordx4 v[44:45], v[40:43], off
	v_lshlrev_b32_e32 v44, 16, v66
	s_nop 0
	v_fma_f32 v40, -v49, v50, 1.0
	v_fmac_f32_e32 v50, v40, v50
	v_and_b32_e32 v42, 0xffff0000, v70
	v_mul_f32_e32 v42, 0xbfb8aa3b, v42
	v_exp_f32_e32 v42, v42
	v_rcp_f32_e32 v40, v48
	s_nop 0
	v_add_f32_e32 v41, 1.0, v42
	v_fmac_f32_e32 v44, v36, v40
	v_lshlrev_b32_e32 v45, 16, v71
	v_mul_f32_e32 v45, 0xbfb8aa3b, v45
	v_exp_f32_e32 v45, v45
	v_rcp_f32_e32 v36, v41
	s_nop 0
	v_add_f32_e32 v40, 1.0, v45
	v_and_b32_e32 v41, 0xffff0000, v66
	v_fmac_f32_e32 v41, v37, v36
	v_and_b32_e32 v45, 0xffff0000, v71
	v_mul_f32_e32 v45, 0xbfb8aa3b, v45
	v_exp_f32_e32 v45, v45
	v_rcp_f32_e32 v36, v40
	s_nop 0
	v_add_f32_e32 v37, 1.0, v45
	v_lshlrev_b32_e32 v40, 16, v67
	v_fmac_f32_e32 v40, v38, v36
	v_lshlrev_b32_e32 v45, 16, v72
	v_mul_f32_e32 v45, 0xbfb8aa3b, v45
	v_exp_f32_e32 v45, v45
	v_rcp_f32_e32 v36, v37
	s_nop 0
	v_add_f32_e32 v38, 1.0, v45
	v_and_b32_e32 v37, 0xffff0000, v67
	v_fmac_f32_e32 v37, v39, v36
	v_and_b32_e32 v45, 0xffff0000, v72
	v_mul_f32_e32 v45, 0xbfb8aa3b, v45
	v_exp_f32_e32 v45, v45
	v_rcp_f32_e32 v36, v38
	s_nop 0
	v_add_f32_e32 v39, 1.0, v45
	v_lshlrev_b32_e32 v38, 16, v68
	v_fmac_f32_e32 v38, v32, v36
	v_lshlrev_b32_e32 v45, 16, v73
	v_mul_f32_e32 v45, 0xbfb8aa3b, v45
	v_exp_f32_e32 v45, v45
	v_rcp_f32_e32 v32, v39
	s_nop 0
	v_add_f32_e32 v36, 1.0, v45
	v_and_b32_e32 v39, 0xffff0000, v68
	v_fmac_f32_e32 v39, v33, v32
	v_and_b32_e32 v45, 0xffff0000, v73
	v_mul_f32_e32 v45, 0xbfb8aa3b, v45
	v_exp_f32_e32 v45, v45
	v_rcp_f32_e32 v32, v36
	s_nop 0
	v_add_f32_e32 v33, 1.0, v45
	v_div_scale_f32 v42, s[4:5], v33, v33, 1.0
	v_rcp_f32_e32 v43, v42
	v_lshlrev_b32_e32 v36, 16, v69
	v_fmac_f32_e32 v36, v34, v32
	v_fma_f32 v32, -v42, v43, 1.0
	v_fmac_f32_e32 v43, v32, v43
	v_div_scale_f32 v32, vcc, 1.0, v33, 1.0
	v_mul_f32_e32 v34, v32, v43
	v_fma_f32 v45, -v42, v34, v32
	v_rcp_f32_e32 v32, v33
	s_nop 0
	v_and_b32_e32 v42, 0xffff0000, v69
	v_fmac_f32_e32 v42, v35, v32
	v_cvt_pk_bf16_f32 v32, v44, v41
	v_cvt_pk_bf16_f32 v34, v38, v39
	v_cvt_pk_bf16_f32 v35, v36, v42
	v_cvt_pk_bf16_f32 v33, v40, v37
	global_store_dwordx4 v[46:47], v[32:35], off offset:256
	s_nop 1
	v_add_u32_e32 v32, 0xa0, v184
	v_mov_b64_e32 v[34:35], s[24:25]
	v_mad_i64_i32 v[34:35], s[4:5], v32, s82, v[34:35]
	v_lshl_add_u64 v[34:35], s[56:57], 1, v[34:35]
	v_lshl_add_u64 v[36:37], v[34:35], 0, v[168:169]
	v_add_co_u32_e32 v34, vcc, 0x5000, v36
	v_ashrrev_i32_e32 v33, 31, v32
	s_nop 0
	v_addc_co_u32_e32 v35, vcc, 0, v37, vcc
	s_waitcnt vmcnt(4)
	v_mov_b32_e32 v56, v222
	v_mov_b32_e32 v57, v223
	v_mov_b32_e32 v58, v224
	v_mov_b32_e32 v59, v225
	v_lshlrev_b64 v[60:61], 12, v[32:33]
	s_and_b64 vcc, exec, s[40:41]
	v_lshl_add_u64 v[34:35], s[42:43], 0, v[60:61]
	s_cbranch_vccnz .LBB0_623
	v_lshl_add_u64 v[38:39], v[34:35], 0, v[168:169]
	global_load_dwordx4 v[62:65], v[38:39], off
.LBB0_623:
	v_lshl_add_u64 v[36:37], v[36:37], 0, s[8:9]
	v_mov_b32_e32 v52, v226
	v_mov_b32_e32 v53, v227
	v_mov_b32_e32 v54, v228
	v_mov_b32_e32 v55, v229
	v_mov_b32_e32 v42, 0
	s_and_b64 vcc, exec, s[40:41]
	v_mov_b32_e32 v50, 0
	v_mov_b32_e32 v51, 0
	v_mov_b32_e32 v48, 0
	v_mov_b32_e32 v49, 0
	s_cbranch_vccnz .LBB0_625
	v_lshl_add_u64 v[34:35], v[34:35], 0, v[168:169]
	global_load_dwordx4 v[48:51], v[34:35], off offset:256
.LBB0_625:
	v_or_b32_e32 v34, 16, v32
	v_mov_b64_e32 v[32:33], s[24:25]
	v_mad_i64_i32 v[32:33], s[4:5], v34, s82, v[32:33]
	v_lshl_add_u64 v[32:33], s[56:57], 1, v[32:33]
	v_lshl_add_u64 v[32:33], v[32:33], 0, v[168:169]
	v_add_co_u32_e32 v36, vcc, 0x5000, v32
	v_ashrrev_i32_e32 v35, 31, v34
	s_nop 0
	v_addc_co_u32_e32 v37, vcc, 0, v33, vcc
	v_mov_b32_e32 v44, v230
	v_mov_b32_e32 v45, v231
	v_mov_b32_e32 v46, v232
	v_mov_b32_e32 v47, v233
	v_lshlrev_b64 v[34:35], 12, v[34:35]
	s_and_b64 vcc, exec, s[40:41]
	v_lshl_add_u64 v[34:35], s[42:43], 0, v[34:35]
	v_mov_b32_e32 v43, 0
	v_mov_b32_e32 v40, 0
	v_mov_b32_e32 v41, 0
	s_cbranch_vccnz .LBB0_627
	v_lshl_add_u64 v[36:37], v[34:35], 0, v[168:169]
	global_load_dwordx4 v[40:43], v[36:37], off
.LBB0_627:
	v_lshl_add_u64 v[32:33], v[32:33], 0, s[8:9]
	v_mov_b32_e32 v36, v234
	v_mov_b32_e32 v37, v235
	v_mov_b32_e32 v38, v236
	v_mov_b32_e32 v39, v237
	s_and_b64 vcc, exec, s[40:41]
	s_cbranch_vccnz .LBB0_629
	v_lshl_add_u64 v[32:33], v[34:35], 0, v[168:169]
	global_load_dwordx4 v[32:35], v[32:33], off offset:256
	s_branch .LBB0_630

.LBB0_630:
	s_waitcnt vmcnt(2)
	v_lshlrev_b32_e32 v66, 16, v56
	v_mul_f32_e32 v66, 0xbfb8aa3b, v66
	v_exp_f32_e32 v66, v66
	v_and_b32_e32 v56, 0xffff0000, v56
	v_mul_f32_e32 v56, 0xbfb8aa3b, v56
	v_exp_f32_e32 v56, v56
	v_add_f32_e32 v66, 1.0, v66
	v_div_scale_f32 v67, s[4:5], v66, v66, 1.0
	v_rcp_f32_e32 v68, v67
	v_div_scale_f32 v69, vcc, 1.0, v66, 1.0
	v_add_f32_e32 v56, 1.0, v56
	v_fma_f32 v70, -v67, v68, 1.0
	v_fmac_f32_e32 v68, v70, v68
	v_mul_f32_e32 v70, v69, v68
	v_fma_f32 v71, -v67, v70, v69
	v_rcp_f32_e32 v66, v66
	s_nop 0
	v_lshlrev_b32_e32 v67, 16, v62
	v_fmac_f32_e32 v67, v28, v66
	v_lshlrev_b32_e32 v70, 16, v57
	v_mul_f32_e32 v70, 0xbfb8aa3b, v70
	v_exp_f32_e32 v70, v70
	v_rcp_f32_e32 v28, v56
	s_nop 0
	v_add_f32_e32 v66, 1.0, v70
	v_div_scale_f32 v68, s[4:5], v66, v66, 1.0
	v_rcp_f32_e32 v69, v68
	v_and_b32_e32 v56, 0xffff0000, v62
	v_fmac_f32_e32 v56, v29, v28
	v_and_b32_e32 v57, 0xffff0000, v57
	v_fma_f32 v28, -v68, v69, 1.0
	v_fmac_f32_e32 v69, v28, v69
	v_mul_f32_e32 v57, 0xbfb8aa3b, v57
	v_exp_f32_e32 v57, v57
	s_nop 0
	v_add_f32_e32 v29, 1.0, v57
	v_rcp_f32_e32 v28, v66
	s_nop 0
	v_lshlrev_b32_e32 v66, 16, v63
	v_fmac_f32_e32 v66, v30, v28
	v_lshlrev_b32_e32 v68, 16, v58
	v_mul_f32_e32 v68, 0xbfb8aa3b, v68
	v_exp_f32_e32 v68, v68
	v_rcp_f32_e32 v28, v29
	s_nop 0
	v_add_f32_e32 v30, 1.0, v68
	v_div_scale_f32 v57, s[4:5], v30, v30, 1.0
	v_rcp_f32_e32 v62, v57
	v_and_b32_e32 v29, 0xffff0000, v63
	v_fmac_f32_e32 v29, v31, v28
	v_and_b32_e32 v58, 0xffff0000, v58
	v_fma_f32 v28, -v57, v62, 1.0
	v_fmac_f32_e32 v62, v28, v62
	v_div_scale_f32 v28, vcc, 1.0, v30, 1.0
	v_mul_f32_e32 v58, 0xbfb8aa3b, v58
	v_mul_f32_e32 v31, v28, v62
	v_exp_f32_e32 v58, v58
	v_fma_f32 v63, -v57, v31, v28
	v_add_f32_e32 v31, 1.0, v58
	v_rcp_f32_e32 v28, v30
	s_nop 0
	v_lshlrev_b32_e32 v30, 16, v64
	v_fmac_f32_e32 v30, v24, v28
	v_lshlrev_b32_e32 v62, 16, v59
	v_mul_f32_e32 v62, 0xbfb8aa3b, v62
	v_exp_f32_e32 v62, v62
	v_rcp_f32_e32 v24, v31
	s_nop 0
	v_add_f32_e32 v28, 1.0, v62
	v_div_scale_f32 v57, s[4:5], v28, v28, 1.0
	v_rcp_f32_e32 v58, v57
	v_and_b32_e32 v31, 0xffff0000, v64
	v_fmac_f32_e32 v31, v25, v24
	v_and_b32_e32 v59, 0xffff0000, v59
	v_fma_f32 v24, -v57, v58, 1.0
	v_fmac_f32_e32 v58, v24, v58
	v_div_scale_f32 v24, vcc, 1.0, v28, 1.0
	v_mul_f32_e32 v59, 0xbfb8aa3b, v59
	v_mul_f32_e32 v25, v24, v58
	v_exp_f32_e32 v59, v59
	v_fma_f32 v62, -v57, v25, v24
	v_add_f32_e32 v25, 1.0, v59
	v_div_scale_f32 v57, s[4:5], v25, v25, 1.0
	v_rcp_f32_e32 v58, v57
	v_rcp_f32_e32 v24, v28
	s_nop 0
	v_lshlrev_b32_e32 v28, 16, v65
	v_fmac_f32_e32 v28, v26, v24
	v_fma_f32 v24, -v57, v58, 1.0
	v_fmac_f32_e32 v58, v24, v58
	v_div_scale_f32 v24, vcc, 1.0, v25, 1.0
	v_mul_f32_e32 v26, v24, v58
	v_fma_f32 v59, -v57, v26, v24
	v_rcp_f32_e32 v24, v25
	s_nop 0
	s_waitcnt vmcnt(1)
	v_lshlrev_b32_e32 v25, 16, v52
	v_and_b32_e32 v57, 0xffff0000, v65
	v_mul_f32_e32 v25, 0xbfb8aa3b, v25
	v_fmac_f32_e32 v57, v27, v24
	v_cvt_pk_bf16_f32 v24, v67, v56
	v_exp_f32_e32 v56, v25
	v_cvt_pk_bf16_f32 v26, v30, v31
	v_cvt_pk_bf16_f32 v25, v66, v29
	v_cvt_pk_bf16_f32 v27, v28, v57
	v_lshl_add_u64 v[28:29], s[58:59], 0, v[60:61]
	v_add_f32_e32 v30, 1.0, v56
	v_div_scale_f32 v31, s[4:5], v30, v30, 1.0
	v_rcp_f32_e32 v56, v31
	v_lshl_add_u64 v[28:29], v[28:29], 0, v[168:169]
	global_store_dwordx4 v[28:29], v[24:27], off
	s_mov_b64 s[18:19], -1
	s_nop 0
	v_fma_f32 v24, -v31, v56, 1.0
	v_fmac_f32_e32 v56, v24, v56
	v_and_b32_e32 v26, 0xffff0000, v52
	v_mul_f32_e32 v26, 0xbfb8aa3b, v26
	v_exp_f32_e32 v26, v26
	v_rcp_f32_e32 v24, v30
	s_nop 0
	v_add_f32_e32 v25, 1.0, v26
	v_lshlrev_b32_e32 v30, 16, v48
	v_fmac_f32_e32 v30, v20, v24
	v_lshlrev_b32_e32 v31, 16, v53
	v_mul_f32_e32 v31, 0xbfb8aa3b, v31
	v_exp_f32_e32 v31, v31
	v_rcp_f32_e32 v20, v25
	s_nop 0
	v_add_f32_e32 v24, 1.0, v31
	v_and_b32_e32 v25, 0xffff0000, v48
	v_fmac_f32_e32 v25, v21, v20
	v_and_b32_e32 v31, 0xffff0000, v53
	v_mul_f32_e32 v31, 0xbfb8aa3b, v31
	v_exp_f32_e32 v31, v31
	v_rcp_f32_e32 v20, v24
	s_nop 0
	v_add_f32_e32 v21, 1.0, v31
	v_lshlrev_b32_e32 v24, 16, v49
	v_fmac_f32_e32 v24, v22, v20
	v_lshlrev_b32_e32 v31, 16, v54
	v_mul_f32_e32 v31, 0xbfb8aa3b, v31
	v_exp_f32_e32 v31, v31
	v_rcp_f32_e32 v20, v21
	s_nop 0
	v_add_f32_e32 v22, 1.0, v31
	v_and_b32_e32 v21, 0xffff0000, v49
	v_fmac_f32_e32 v21, v23, v20
	v_and_b32_e32 v31, 0xffff0000, v54
	v_mul_f32_e32 v31, 0xbfb8aa3b, v31
	v_exp_f32_e32 v31, v31
	v_rcp_f32_e32 v20, v22
	s_nop 0
	v_add_f32_e32 v23, 1.0, v31
	v_lshlrev_b32_e32 v22, 16, v50
	v_fmac_f32_e32 v22, v16, v20
	v_lshlrev_b32_e32 v31, 16, v55
	v_mul_f32_e32 v31, 0xbfb8aa3b, v31
	v_exp_f32_e32 v31, v31
	v_rcp_f32_e32 v16, v23
	s_nop 0
	v_add_f32_e32 v20, 1.0, v31
	v_and_b32_e32 v23, 0xffff0000, v50
	v_fmac_f32_e32 v23, v17, v16
	v_and_b32_e32 v31, 0xffff0000, v55
	v_mul_f32_e32 v31, 0xbfb8aa3b, v31
	v_exp_f32_e32 v31, v31
	v_rcp_f32_e32 v16, v20
	s_nop 0
	v_add_f32_e32 v17, 1.0, v31
	v_div_scale_f32 v26, s[4:5], v17, v17, 1.0
	v_rcp_f32_e32 v27, v26
	v_lshlrev_b32_e32 v20, 16, v51
	v_fmac_f32_e32 v20, v18, v16
	v_fma_f32 v16, -v26, v27, 1.0
	v_fmac_f32_e32 v27, v16, v27
	v_div_scale_f32 v16, vcc, 1.0, v17, 1.0
	v_mul_f32_e32 v18, v16, v27
	v_fma_f32 v31, -v26, v18, v16
	v_rcp_f32_e32 v16, v17
	s_nop 0
	s_waitcnt vmcnt(2)
	v_lshlrev_b32_e32 v17, 16, v44
	v_mul_f32_e32 v17, 0xbfb8aa3b, v17
	v_exp_f32_e32 v18, v17
	v_cvt_pk_bf16_f32 v17, v24, v21
	v_and_b32_e32 v26, 0xffff0000, v51
	v_fmac_f32_e32 v26, v19, v16
	v_add_f32_e32 v21, 1.0, v18
	v_div_scale_f32 v24, s[4:5], v21, v21, 1.0
	v_cvt_pk_bf16_f32 v16, v30, v25
	v_rcp_f32_e32 v25, v24
	v_cvt_pk_bf16_f32 v18, v22, v23
	v_cvt_pk_bf16_f32 v19, v20, v26
	global_store_dwordx4 v[28:29], v[16:19], off offset:256
	v_lshlrev_b32_e32 v20, 16, v40
	s_nop 0
	v_fma_f32 v16, -v24, v25, 1.0
	v_fmac_f32_e32 v25, v16, v25
	v_and_b32_e32 v18, 0xffff0000, v44
	v_mul_f32_e32 v18, 0xbfb8aa3b, v18
	v_exp_f32_e32 v18, v18
	v_rcp_f32_e32 v16, v21
	s_nop 0
	v_add_f32_e32 v17, 1.0, v18
	v_fmac_f32_e32 v20, v12, v16
	v_lshlrev_b32_e32 v21, 16, v45
	v_mul_f32_e32 v21, 0xbfb8aa3b, v21
	v_exp_f32_e32 v21, v21
	v_rcp_f32_e32 v12, v17
	s_nop 0
	v_add_f32_e32 v16, 1.0, v21
	v_and_b32_e32 v17, 0xffff0000, v40
	v_fmac_f32_e32 v17, v13, v12
	v_and_b32_e32 v21, 0xffff0000, v45
	v_mul_f32_e32 v21, 0xbfb8aa3b, v21
	v_exp_f32_e32 v21, v21
	v_rcp_f32_e32 v12, v16
	s_nop 0
	v_add_f32_e32 v13, 1.0, v21
	v_lshlrev_b32_e32 v16, 16, v41
	v_fmac_f32_e32 v16, v14, v12
	v_lshlrev_b32_e32 v21, 16, v46
	v_mul_f32_e32 v21, 0xbfb8aa3b, v21
	v_exp_f32_e32 v21, v21
	v_rcp_f32_e32 v12, v13
	s_nop 0
	v_add_f32_e32 v14, 1.0, v21
	v_and_b32_e32 v13, 0xffff0000, v41
	v_fmac_f32_e32 v13, v15, v12
	v_and_b32_e32 v21, 0xffff0000, v46
	v_mul_f32_e32 v21, 0xbfb8aa3b, v21
	v_exp_f32_e32 v21, v21
	v_rcp_f32_e32 v12, v14
	s_nop 0
	v_add_f32_e32 v15, 1.0, v21
	v_lshlrev_b32_e32 v14, 16, v42
	v_fmac_f32_e32 v14, v8, v12
	v_lshlrev_b32_e32 v21, 16, v47
	v_mul_f32_e32 v21, 0xbfb8aa3b, v21
	v_exp_f32_e32 v21, v21
	v_rcp_f32_e32 v8, v15
	s_nop 0
	v_add_f32_e32 v12, 1.0, v21
	v_and_b32_e32 v15, 0xffff0000, v42
	v_fmac_f32_e32 v15, v9, v8
	v_and_b32_e32 v21, 0xffff0000, v47
	v_mul_f32_e32 v21, 0xbfb8aa3b, v21
	v_exp_f32_e32 v21, v21
	v_rcp_f32_e32 v8, v12
	s_nop 0
	v_add_f32_e32 v9, 1.0, v21
	v_div_scale_f32 v18, s[4:5], v9, v9, 1.0
	v_rcp_f32_e32 v19, v18
	v_lshlrev_b32_e32 v12, 16, v43
	v_fmac_f32_e32 v12, v10, v8
	s_mov_b64 s[4:5], 0xb0000
	v_fma_f32 v8, -v18, v19, 1.0
	v_fmac_f32_e32 v19, v8, v19
	v_div_scale_f32 v8, vcc, 1.0, v9, 1.0
	v_mul_f32_e32 v10, v8, v19
	v_fma_f32 v21, -v18, v10, v8
	v_rcp_f32_e32 v8, v9
	s_nop 0
	v_and_b32_e32 v18, 0xffff0000, v43
	v_fmac_f32_e32 v18, v11, v8
	s_waitcnt vmcnt(2)
	v_lshlrev_b32_e32 v11, 16, v36
	v_mul_f32_e32 v11, 0xbfb8aa3b, v11
	v_cvt_pk_bf16_f32 v9, v16, v13
	v_exp_f32_e32 v16, v11
	v_cvt_pk_bf16_f32 v11, v12, v18
	v_lshl_add_u64 v[12:13], v[154:155], 0, v[168:169]
	v_cvt_pk_bf16_f32 v8, v20, v17
	v_add_f32_e32 v16, 1.0, v16
	v_cvt_pk_bf16_f32 v10, v14, v15
	v_lshl_add_u64 v[14:15], v[12:13], 0, s[4:5]
	v_div_scale_f32 v17, s[4:5], v16, v16, 1.0
	v_rcp_f32_e32 v18, v17
	s_mov_b32 s4, 0xb0000
	v_add_co_u32_e32 v12, vcc, s4, v12
	s_nop 1
	v_addc_co_u32_e32 v13, vcc, 0, v13, vcc
	global_store_dwordx4 v[12:13], v[8:11], off
	v_lshlrev_b32_e32 v12, 16, v32
	s_nop 0
	v_fma_f32 v8, -v17, v18, 1.0
	v_fmac_f32_e32 v18, v8, v18
	v_and_b32_e32 v10, 0xffff0000, v36
	v_mul_f32_e32 v10, 0xbfb8aa3b, v10
	v_exp_f32_e32 v10, v10
	v_rcp_f32_e32 v8, v16
	s_nop 0
	v_add_f32_e32 v9, 1.0, v10
	v_fmac_f32_e32 v12, v4, v8
	v_lshlrev_b32_e32 v13, 16, v37
	v_mul_f32_e32 v13, 0xbfb8aa3b, v13
	v_exp_f32_e32 v13, v13
	v_rcp_f32_e32 v4, v9
	s_nop 0
	v_add_f32_e32 v8, 1.0, v13
	v_and_b32_e32 v9, 0xffff0000, v32
	v_fmac_f32_e32 v9, v5, v4
	v_and_b32_e32 v13, 0xffff0000, v37
	v_mul_f32_e32 v13, 0xbfb8aa3b, v13
	v_exp_f32_e32 v13, v13
	v_rcp_f32_e32 v4, v8
	s_nop 0
	v_add_f32_e32 v5, 1.0, v13
	v_lshlrev_b32_e32 v8, 16, v33
	v_fmac_f32_e32 v8, v6, v4
	v_lshlrev_b32_e32 v13, 16, v38
	v_mul_f32_e32 v13, 0xbfb8aa3b, v13
	v_exp_f32_e32 v13, v13
	v_rcp_f32_e32 v4, v5
	s_nop 0
	v_add_f32_e32 v6, 1.0, v13
	v_and_b32_e32 v5, 0xffff0000, v33
	v_fmac_f32_e32 v5, v7, v4
	v_and_b32_e32 v13, 0xffff0000, v38
	v_mul_f32_e32 v13, 0xbfb8aa3b, v13
	v_exp_f32_e32 v13, v13
	v_rcp_f32_e32 v4, v6
	s_nop 0
	v_add_f32_e32 v7, 1.0, v13
	v_lshlrev_b32_e32 v6, 16, v34
	v_fmac_f32_e32 v6, v0, v4
	v_lshlrev_b32_e32 v13, 16, v39
	v_mul_f32_e32 v13, 0xbfb8aa3b, v13
	v_exp_f32_e32 v13, v13
	v_rcp_f32_e32 v0, v7
	s_nop 0
	v_add_f32_e32 v4, 1.0, v13
	v_and_b32_e32 v7, 0xffff0000, v34
	v_fmac_f32_e32 v7, v1, v0
	v_and_b32_e32 v13, 0xffff0000, v39
	v_mul_f32_e32 v13, 0xbfb8aa3b, v13
	v_exp_f32_e32 v13, v13
	v_rcp_f32_e32 v0, v4
	s_nop 0
	v_add_f32_e32 v1, 1.0, v13
	v_div_scale_f32 v10, s[4:5], v1, v1, 1.0
	v_rcp_f32_e32 v11, v10
	v_lshlrev_b32_e32 v4, 16, v35
	v_fmac_f32_e32 v4, v2, v0
	v_fma_f32 v0, -v10, v11, 1.0
	v_fmac_f32_e32 v11, v0, v11
	v_div_scale_f32 v0, vcc, 1.0, v1, 1.0
	v_mul_f32_e32 v2, v0, v11
	v_fma_f32 v13, -v10, v2, v0
	v_fmac_f32_e32 v2, v13, v11
	s_nop 0
	s_nop 0
	v_rcp_f32_e32 v0, v1
	s_nop 0
	v_and_b32_e32 v10, 0xffff0000, v35
	s_andn2_b64 vcc, exec, s[38:39]
	v_fmac_f32_e32 v10, v3, v0
	v_cvt_pk_bf16_f32 v0, v12, v9
	v_cvt_pk_bf16_f32 v1, v8, v5
	v_cvt_pk_bf16_f32 v2, v6, v7
	v_cvt_pk_bf16_f32 v3, v4, v10
	global_store_dwordx4 v[14:15], v[0:3], off offset:256
	s_cbranch_vccnz .LBB0_585
	s_andn2_b64 vcc, exec, s[0:1]
	s_cbranch_vccnz .LBB0_584
	s_barrier
	s_branch .LBB0_584

	.amdhsa_kernel _Z14fwd_megakernel6Params
		.amdhsa_group_segment_fixed_size 0
		.amdhsa_private_segment_fixed_size 0
		.amdhsa_kernarg_size 544
		.amdhsa_user_sgpr_count 2
		.amdhsa_user_sgpr_dispatch_ptr 0
		.amdhsa_user_sgpr_queue_ptr 0
		.amdhsa_user_sgpr_kernarg_segment_ptr 1
		.amdhsa_user_sgpr_dispatch_id 0
		.amdhsa_user_sgpr_kernarg_preload_length 0
		.amdhsa_user_sgpr_kernarg_preload_offset 0
		.amdhsa_user_sgpr_private_segment_size 0
		.amdhsa_uses_dynamic_stack 0
		.amdhsa_enable_private_segment 0
		.amdhsa_system_sgpr_workgroup_id_x 1
		.amdhsa_system_sgpr_workgroup_id_y 0
		.amdhsa_system_sgpr_workgroup_id_z 0
		.amdhsa_system_sgpr_workgroup_info 0
		.amdhsa_system_vgpr_workitem_id 2
		.amdhsa_next_free_vgpr 254
		.amdhsa_next_free_sgpr 102
		.amdhsa_accum_offset 256
		.amdhsa_reserve_vcc 1
		.amdhsa_float_round_mode_32 0
		.amdhsa_float_round_mode_16_64 0
		.amdhsa_float_denorm_mode_32 3
		.amdhsa_float_denorm_mode_16_64 3
		.amdhsa_dx10_clamp 1
		.amdhsa_ieee_mode 1
		.amdhsa_fp16_overflow 0
		.amdhsa_tg_split 0
		.amdhsa_exception_fp_ieee_invalid_op 0
		.amdhsa_exception_fp_denorm_src 0
		.amdhsa_exception_fp_ieee_div_zero 0
		.amdhsa_exception_fp_ieee_overflow 0
		.amdhsa_exception_fp_ieee_underflow 0
		.amdhsa_exception_fp_ieee_inexact 0
		.amdhsa_exception_int_div_zero 0
	.end_amdhsa_kernel

amdhsa.kernels:
  - .agpr_count:     0
    .args:
      - .offset:         0
        .size:           288
        .value_kind:     by_value
      - .offset:         288
        .size:           4
        .value_kind:     hidden_block_count_x
      - .offset:         292
        .size:           4
        .value_kind:     hidden_block_count_y
      - .offset:         296
        .size:           4
        .value_kind:     hidden_block_count_z
      - .offset:         300
        .size:           2
        .value_kind:     hidden_group_size_x
      - .offset:         302
        .size:           2
        .value_kind:     hidden_group_size_y
      - .offset:         304
        .size:           2
        .value_kind:     hidden_group_size_z
      - .offset:         306
        .size:           2
        .value_kind:     hidden_remainder_x
      - .offset:         308
        .size:           2
        .value_kind:     hidden_remainder_y
      - .offset:         310
        .size:           2
        .value_kind:     hidden_remainder_z
      - .offset:         328
        .size:           8
        .value_kind:     hidden_global_offset_x
      - .offset:         336
        .size:           8
        .value_kind:     hidden_global_offset_y
      - .offset:         344
        .size:           8
        .value_kind:     hidden_global_offset_z
      - .offset:         352
        .size:           2
        .value_kind:     hidden_grid_dims
      - .offset:         376
        .size:           8
        .value_kind:     hidden_multigrid_sync_arg
      - .offset:         408
        .size:           4
        .value_kind:     hidden_dynamic_lds_size
    .group_segment_fixed_size: 0
    .kernarg_segment_align: 8
    .kernarg_segment_size: 544
    .language:       OpenCL C
    .language_version:
      - 2
      - 0
    .max_flat_workgroup_size: 512
    .name:           _Z14fwd_megakernel6Params
    .private_segment_fixed_size: 0
    .sgpr_count:     108
    .sgpr_spill_count: 110
    .symbol:         _Z14fwd_megakernel6Params.kd
    .uniform_work_group_size: 1
    .uses_dynamic_stack: false
    .vgpr_count:     254
    .vgpr_spill_count: 0
    .wavefront_size: 64
